# SCAN sample-scan: prefetch next pb h0 block into spare regs one iteration ahead (counted vmcnt(12), copy at latch)
# baseline (speedup 1.0000x reference)
; #define MFMA16(a, b, c) __builtin_amdgcn_mfma_f32_16x16x32_bf16((a), (b), (c), 0, 0, 0)
; #define MFMA16(a, b, c) __builtin_amdgcn_mfma_f32_16x16x32_bf16((a), (b), (c), 0, 0, 0)
; __device__ __forceinline__ void scan_sample_wave(const Ctx& c, int bs, int h) {
;     ...
;     for (int pb = 0; pb < 4; ++pb) {
;         const int p = 16 * pb + c16;
;         f32x4 h0[8];
; #pragma unroll
;         for (int nt = 0; nt < 8; ++nt) h0[nt] = *(const f32x4*)(h0base + (size_t)p * 128 + 16 * nt + 4 * q);
;     ...
; #pragma unroll
;         for (int nt = 0; nt < 8; ++nt) {
;             const bf16x8 bsf = tr_frag8(L + W_BS, SROW, 16 * nt, lane);
;             const f32x4 S = MFMA16(bsf, xsf, ((f32x4){0.f, 0.f, 0.f, 0.f}));
;             *(f32x4*)(hobase + (size_t)p * 128 + 16 * nt + 4 * q) = h0[nt] * cdec + S;
;         }
;     }
.LBB0_227:
	s_or_b64 exec, exec, s[24:25]
	s_nop 4
	ds_read_b64_tr_b16 v[62:63], v93 offset:8704
	ds_read_b64_tr_b16 v[64:65], v93 offset:9792
	v_mov_b32_e32 v79, v78
	v_lshl_add_u64 v[60:61], v[72:73], 0, s[22:23]
	s_add_u32 s22, s22, 0x2000
	s_waitcnt lgkmcnt(1)
	v_cndmask_b32_e64 v62, v62, 0, s[42:43]
	v_cndmask_b32_e64 v63, v63, 0, s[42:43]
	s_waitcnt lgkmcnt(0)
	v_cndmask_b32_e64 v64, v64, 0, s[42:43]
	v_cndmask_b32_e64 v65, v65, 0, s[42:43]
	s_addc_u32 s23, s23, 0
	v_add_u32_e32 v100, 32, v100
	v_mfma_f32_16x16x32_bf16 v[62:65], v[62:65], v[28:31], 0
	v_add_u32_e32 v99, 32, v99
	v_lshl_add_u64 v[82:83], v[82:83], 0, 32
	s_cmpk_lg_u32 s22, 0x8000
	s_nop 4
	v_pk_fma_f32 v[58:59], v[78:79], v[58:59], v[64:65]
	v_pk_fma_f32 v[56:57], v[80:81], v[56:57], v[62:63]
	global_store_dwordx4 v[60:61], v[56:59], off offset:-256
	ds_read_b64_tr_b16 v[56:57], v93 offset:8736
	ds_read_b64_tr_b16 v[58:59], v93 offset:9824
	s_waitcnt lgkmcnt(1)
	v_cndmask_b32_e64 v56, v56, 0, s[42:43]
	v_cndmask_b32_e64 v57, v57, 0, s[42:43]
	s_waitcnt lgkmcnt(0)
	v_cndmask_b32_e64 v58, v58, 0, s[42:43]
	v_cndmask_b32_e64 v59, v59, 0, s[42:43]
	s_nop 1
	v_mfma_f32_16x16x32_bf16 v[56:59], v[56:59], v[28:31], 0
	s_nop 7
	v_pk_fma_f32 v[54:55], v[78:79], v[54:55], v[58:59]
	v_pk_fma_f32 v[52:53], v[80:81], v[52:53], v[56:57]
	global_store_dwordx4 v[60:61], v[52:55], off offset:-192
	ds_read_b64_tr_b16 v[52:53], v93 offset:8768
	ds_read_b64_tr_b16 v[54:55], v93 offset:9856
	s_waitcnt lgkmcnt(1)
	v_cndmask_b32_e64 v52, v52, 0, s[42:43]
	v_cndmask_b32_e64 v53, v53, 0, s[42:43]
	s_waitcnt lgkmcnt(0)
	v_cndmask_b32_e64 v54, v54, 0, s[42:43]
	v_cndmask_b32_e64 v55, v55, 0, s[42:43]
	s_nop 1
	v_mfma_f32_16x16x32_bf16 v[52:55], v[52:55], v[28:31], 0
	s_nop 7
	v_pk_fma_f32 v[50:51], v[78:79], v[50:51], v[54:55]
	v_pk_fma_f32 v[48:49], v[80:81], v[48:49], v[52:53]
	global_store_dwordx4 v[60:61], v[48:51], off offset:-128
	ds_read_b64_tr_b16 v[48:49], v93 offset:8800
	ds_read_b64_tr_b16 v[50:51], v93 offset:9888
	s_waitcnt lgkmcnt(1)
	v_cndmask_b32_e64 v48, v48, 0, s[42:43]
	v_cndmask_b32_e64 v49, v49, 0, s[42:43]
	s_waitcnt lgkmcnt(0)
	v_cndmask_b32_e64 v50, v50, 0, s[42:43]
	v_cndmask_b32_e64 v51, v51, 0, s[42:43]
	s_nop 1
	v_mfma_f32_16x16x32_bf16 v[48:51], v[48:51], v[28:31], 0
	s_nop 7
	v_pk_fma_f32 v[46:47], v[78:79], v[46:47], v[50:51]
	v_pk_fma_f32 v[44:45], v[80:81], v[44:45], v[48:49]
	global_store_dwordx4 v[60:61], v[44:47], off offset:-64
	ds_read_b64_tr_b16 v[44:45], v93 offset:8832
	ds_read_b64_tr_b16 v[46:47], v93 offset:9920
	s_waitcnt lgkmcnt(1)
	v_cndmask_b32_e64 v44, v44, 0, s[42:43]
	v_cndmask_b32_e64 v45, v45, 0, s[42:43]
	s_waitcnt lgkmcnt(0)
	v_cndmask_b32_e64 v46, v46, 0, s[42:43]
	v_cndmask_b32_e64 v47, v47, 0, s[42:43]
	s_nop 1
	v_mfma_f32_16x16x32_bf16 v[44:47], v[44:47], v[28:31], 0
	s_nop 7
	v_pk_fma_f32 v[42:43], v[78:79], v[42:43], v[46:47]
	v_pk_fma_f32 v[40:41], v[80:81], v[40:41], v[44:45]
	global_store_dwordx4 v[60:61], v[40:43], off
	ds_read_b64_tr_b16 v[40:41], v93 offset:8864
	ds_read_b64_tr_b16 v[42:43], v93 offset:9952
	s_waitcnt lgkmcnt(1)
	v_cndmask_b32_e64 v40, v40, 0, s[42:43]
	v_cndmask_b32_e64 v41, v41, 0, s[42:43]
	s_waitcnt lgkmcnt(0)
	v_cndmask_b32_e64 v42, v42, 0, s[42:43]
	v_cndmask_b32_e64 v43, v43, 0, s[42:43]
	s_nop 1
	v_mfma_f32_16x16x32_bf16 v[40:43], v[40:43], v[28:31], 0
	s_nop 7
	v_pk_fma_f32 v[38:39], v[78:79], v[38:39], v[42:43]
	v_pk_fma_f32 v[36:37], v[80:81], v[36:37], v[40:41]
	global_store_dwordx4 v[60:61], v[36:39], off offset:64
	ds_read_b64_tr_b16 v[36:37], v93 offset:8896
	ds_read_b64_tr_b16 v[38:39], v93 offset:9984
	s_waitcnt lgkmcnt(1)
	v_cndmask_b32_e64 v36, v36, 0, s[42:43]
	v_cndmask_b32_e64 v37, v37, 0, s[42:43]
	s_waitcnt lgkmcnt(0)
	v_cndmask_b32_e64 v38, v38, 0, s[42:43]
	v_cndmask_b32_e64 v39, v39, 0, s[42:43]
	s_nop 1
	v_mfma_f32_16x16x32_bf16 v[36:39], v[36:39], v[28:31], 0
	s_nop 7
	v_pk_fma_f32 v[34:35], v[78:79], v[34:35], v[38:39]
	v_pk_fma_f32 v[32:33], v[80:81], v[32:33], v[36:37]
	global_store_dwordx4 v[60:61], v[32:35], off offset:128
	ds_read_b64_tr_b16 v[32:33], v93 offset:8928
	ds_read_b64_tr_b16 v[34:35], v93 offset:10016
	s_waitcnt lgkmcnt(1)
	v_cndmask_b32_e64 v32, v32, 0, s[42:43]
	v_cndmask_b32_e64 v33, v33, 0, s[42:43]
	s_waitcnt lgkmcnt(0)
	v_cndmask_b32_e64 v34, v34, 0, s[42:43]
	v_cndmask_b32_e64 v35, v35, 0, s[42:43]
	s_nop 1
	v_mfma_f32_16x16x32_bf16 v[28:31], v[32:35], v[28:31], 0
	s_nop 7
	v_pk_fma_f32 v[26:27], v[78:79], v[26:27], v[30:31]
	v_pk_fma_f32 v[24:25], v[80:81], v[24:25], v[28:29]
	global_store_dwordx4 v[60:61], v[24:27], off offset:192
	s_cbranch_scc0 .LBB0_213
	s_waitcnt vmcnt(12)
	v_mov_b64_e32 v[56:57], v[104:105]
	v_mov_b64_e32 v[58:59], v[106:107]
	v_mov_b64_e32 v[52:53], v[108:109]
	v_mov_b64_e32 v[54:55], v[110:111]
	v_mov_b64_e32 v[48:49], v[112:113]
	v_mov_b64_e32 v[50:51], v[114:115]
	v_mov_b64_e32 v[44:45], v[116:117]
	v_mov_b64_e32 v[46:47], v[118:119]
	v_mov_b64_e32 v[40:41], v[120:121]
	v_mov_b64_e32 v[42:43], v[122:123]
	v_mov_b64_e32 v[36:37], v[124:125]
	v_mov_b64_e32 v[38:39], v[126:127]
	v_mov_b64_e32 v[32:33], v[128:129]
	v_mov_b64_e32 v[34:35], v[130:131]
	v_mov_b64_e32 v[24:25], v[132:133]
	v_mov_b64_e32 v[26:27], v[134:135]
	s_branch .Lpb_top2

; #define LAS __attribute__((address_space(3)))
; __device__ __forceinline__ unsigned f2bf(float f) { unsigned u = __builtin_bit_cast(unsigned, f); return (u + 0x7fffu + ((u >> 16) & 1u)) >> 16; }
; __device__ __forceinline__ unsigned cvt_pk_bf16(float lo, float hi) { f32x2 v = {lo, hi}; bf16x2_t b = __builtin_convertvector(v, bf16x2_t); return __builtin_bit_cast(unsigned, b); }
; __device__ __forceinline__ float bflo(unsigned w) { return __uint_as_float(w << 16); }
; __device__ __forceinline__ float bfhi(unsigned w) { return __uint_as_float(w & 0xffff0000u); }
; #define MFMA16(a, b, c) __builtin_amdgcn_mfma_f32_16x16x32_bf16((a), (b), (c), 0, 0, 0)
; __device__ __forceinline__ u32x2 tr_read(LAS unsigned char* p) { return __builtin_bit_cast(u32x2, __builtin_amdgcn_ds_read_tr16_b64_v4i16((LAS v4i16_t*)p)); }
; __device__ __forceinline__ void scan_sample_wave(const Ctx& c, int bs, int h) {
;     ...
;     for (int pb = 0; pb < 4; ++pb) {
;         const int p = 16 * pb + c16;
;         f32x4 h0[8];
; #pragma unroll
;         for (int nt = 0; nt < 8; ++nt) h0[nt] = *(const f32x4*)(h0base + (size_t)p * 128 + 16 * nt + 4 * q);
;         const bf16x8 xsf = tr_frag8(L + W_X, XROW, 16 * pb, lane);
;         f32x4 yd = MFMA16(wf, xsf, ((f32x4){0.f, 0.f, 0.f, 0.f}));
;         f32x4 yo = (f32x4){0.f, 0.f, 0.f, 0.f};
; #pragma unroll
;         for (int a = 0; a < 4; ++a) {
;             const u32x2 clo = *(const LAS u32x2*)(L + W_C + c16 * SROW + (32 * a + 4 * q) * 2), chi = *(const LAS u32x2*)(L + W_C + c16 * SROW + (32 * a + 16 + 4 * q) * 2);
;             u32x4 av; av.x = clo.x; av.y = clo.y; av.z = chi.x; av.w = chi.y;
;             u32x4 bv; bv.x = cvt_pk_bf16(h0[2 * a][0], h0[2 * a][1]); bv.y = cvt_pk_bf16(h0[2 * a][2], h0[2 * a][3]); bv.z = cvt_pk_bf16(h0[2 * a + 1][0], h0[2 * a + 1][1]); bv.w = cvt_pk_bf16(h0[2 * a + 1][2], h0[2 * a + 1][3]);
;             yo = MFMA16(__builtin_bit_cast(bf16x8, av), __builtin_bit_cast(bf16x8, bv), yo);
;         }
;         {
;             const u32x2 xr = tr_read(L + W_X + (4 * (q & 1) + ((lane >> 2) & 3)) * XROW + (16 * pb + 4 * (lane & 3)) * 2);
;             const float xs[4] = {bflo(xr.x), bfhi(xr.x), bflo(xr.y), bfhi(xr.y)};
;             if (q < 2) {
; #pragma unroll
;                 for (int r = 0; r < 4; ++r) { const float y = yd[r] + el[r] * yo[r] + Dh * xs[r]; XBC[(r0 + 4 * q + r) * CONVD + h * 64 + p] = (bf16_t)f2bf(y); }
.Lpb_top2:
	s_cmpk_eq_u32 s22, 0x6000
	s_cbranch_scc1 .Lpb_nopf
	v_lshl_add_u64 v[136:137], v[74:75], 0, s[22:23]
	v_add_co_u32_e32 v136, vcc, 0x2000, v136
	s_nop 1
	v_addc_co_u32_e32 v137, vcc, 0, v137, vcc
	global_load_dwordx4 v[104:107], v[136:137], off
	global_load_dwordx4 v[108:111], v[136:137], off offset:64
	global_load_dwordx4 v[112:115], v[136:137], off offset:128
	global_load_dwordx4 v[116:119], v[136:137], off offset:192
	global_load_dwordx4 v[120:123], v[136:137], off offset:256
	global_load_dwordx4 v[124:127], v[136:137], off offset:320
	global_load_dwordx4 v[128:131], v[136:137], off offset:384
	global_load_dwordx4 v[132:135], v[136:137], off offset:448
.Lpb_nopf:
	v_add_u32_e32 v28, 0xfffffdc0, v99
	ds_read_b64_tr_b16 v[28:29], v28
	ds_read_b64_tr_b16 v[30:31], v99
	ds_read_b64_tr_b16 v[84:85], v100
	s_waitcnt lgkmcnt(2)
	v_cndmask_b32_e64 v28, v28, 0, s[42:43]
	v_cndmask_b32_e64 v29, v29, 0, s[42:43]
	s_waitcnt lgkmcnt(1)
	v_cndmask_b32_e64 v30, v30, 0, s[42:43]
	v_cndmask_b32_e64 v31, v31, 0, s[42:43]
	s_waitcnt vmcnt(15)
	v_cvt_pk_bf16_f32 v60, v56, v57
	v_cvt_pk_bf16_f32 v61, v58, v59
	s_waitcnt vmcnt(14)
	v_cvt_pk_bf16_f32 v62, v52, v53
	v_cvt_pk_bf16_f32 v63, v54, v55
	s_waitcnt vmcnt(13)
	v_cvt_pk_bf16_f32 v64, v48, v49
	v_cvt_pk_bf16_f32 v65, v50, v51
	v_mfma_f32_16x16x32_bf16 v[60:63], v[8:11], v[60:63], 0
	s_waitcnt vmcnt(12)
	v_cvt_pk_bf16_f32 v66, v44, v45
	v_cvt_pk_bf16_f32 v67, v46, v47
	s_nop 1
	v_mfma_f32_16x16x32_bf16 v[60:63], v[12:15], v[64:67], v[60:63]
	s_waitcnt vmcnt(11)
	v_cvt_pk_bf16_f32 v64, v40, v41
	v_cvt_pk_bf16_f32 v65, v42, v43
	s_waitcnt vmcnt(10)
	v_cvt_pk_bf16_f32 v66, v36, v37
	v_cvt_pk_bf16_f32 v67, v38, v39
	s_nop 1
	v_mfma_f32_16x16x32_bf16 v[60:63], v[16:19], v[64:67], v[60:63]
	s_waitcnt vmcnt(9)
	v_cvt_pk_bf16_f32 v64, v32, v33
	v_cvt_pk_bf16_f32 v65, v34, v35
	s_waitcnt vmcnt(8)
	v_cvt_pk_bf16_f32 v66, v24, v25
	v_cvt_pk_bf16_f32 v67, v26, v27
	s_nop 1
	v_mfma_f32_16x16x32_bf16 v[64:67], v[20:23], v[64:67], v[60:63]
	v_mfma_f32_16x16x32_bf16 v[60:63], v[4:7], v[28:31], 0
	s_and_saveexec_b64 s[24:25], s[4:5]
	s_cbranch_execz .LBB0_227
	s_waitcnt lgkmcnt(0)
	v_and_b32_e32 v101, 0xffff0000, v84
	v_lshlrev_b32_e32 v84, 16, v84
	s_nop 2
	v_fma_f32 v60, v95, v64, v60
	v_fmac_f32_e32 v60, v77, v84
	v_bfe_u32 v64, v60, 16, 1
	v_add3_u32 v60, v60, v64, s31
	global_store_short_d16_hi v[82:83], v60, off
	v_fma_f32 v60, v96, v65, v61
	v_fmac_f32_e32 v60, v77, v101
	v_bfe_u32 v61, v60, 16, 1
	v_add3_u32 v64, v60, v61, s31
	v_add_co_u32_e32 v60, vcc, s34, v82
	v_and_b32_e32 v79, 0xffff0000, v85
	s_nop 0
	v_addc_co_u32_e32 v61, vcc, 0, v83, vcc
	v_lshlrev_b32_e32 v85, 16, v85
	global_store_short_d16_hi v[60:61], v64, off offset:2048
	v_fma_f32 v60, v97, v66, v62
	v_fmac_f32_e32 v60, v77, v85
	v_bfe_u32 v61, v60, 16, 1
	v_add3_u32 v62, v60, v61, s31
	v_add_co_u32_e32 v60, vcc, 0x3000, v82
	v_fmac_f32_e32 v63, v98, v67
	s_nop 0
	v_addc_co_u32_e32 v61, vcc, 0, v83, vcc
	v_fmac_f32_e32 v63, v77, v79
	global_store_short_d16_hi v[60:61], v62, off
	v_bfe_u32 v60, v63, 16, 1
	v_add3_u32 v62, v63, v60, s31
	v_add_co_u32_e32 v60, vcc, 0x4000, v82
	s_nop 1
	v_addc_co_u32_e32 v61, vcc, 0, v83, vcc
	global_store_short_d16_hi v[60:61], v62, off offset:2048
	s_branch .LBB0_227
